# v43 + stacked minor tweaks: K-read hoist, FoX pointer bases, fk-first wait, K-loop back-edge rotation, redundant lgkmcnt removal
# speedup vs baseline: 1.0050x; 1.0050x over previous
; #define PG8_STAGE(bufoff, gbase, voff) do { _Pragma("unroll") for (int _i = 0; _i < 2; ++_i) \
;         __builtin_amdgcn_global_load_lds((const unsigned*)((const char*)(gbase) + (voff)[_i]), (LAS unsigned*)(lds + (bufoff) + ldsw + _i * 8192), 16, 0, 0); } while (0)
; #define PG8_LDA(dst, b, h) do { _Pragma("unroll") for (int m = 0; m < 4; ++m) _Pragma("unroll") for (int k = 0; k < 2; ++k) dst[m][k] = *(const LAS bf16x8*)(lds + PG8_SA(b, h) + aoff + m * 2048 + k * 1024); } while (0)
; #define PG8_LDB(dst, b, h) do { _Pragma("unroll") for (int n = 0; n < 2; ++n) _Pragma("unroll") for (int k = 0; k < 2; ++k) dst[n][k] = *(const LAS bf16x8*)(lds + PG8_SB(b, h) + boff + n * 2048 + k * 1024); } while (0)
; #define PG8_WAIT_V(n) asm volatile("s_waitcnt vmcnt(" #n ")" ::: "memory")
; #define PG8_WAIT_L(n) asm volatile("s_waitcnt lgkmcnt(" #n ")" ::: "memory")
; #define PG8_BAR __builtin_amdgcn_s_barrier()
; #define PG8_SCHED __builtin_amdgcn_sched_barrier(0)
; template <class Epi, class Sched, bool HALFN = false>
; __device__ __forceinline__ void gemm_phase(LAS unsigned char* lds, const Gemm g, const Sched& S, const Epi& E, int wave_s) {
;     ...
;         const bool has_next = S.next(ui + 1, nxt);
;         const char* nA = has_next ? (const char*)g.A + (size_t)nxt.z * g.zA * 2 + (size_t)nxt.pm * tstep : cA; const char* nB = has_next ? (const char*)g.Bt + (size_t)nxt.z * g.zB * 2 + (size_t)nxt.pn * (HALFN ? hstep : tstep) : cB;
;         for (int t = 0; t < nt; t += 2) {
;             const bool last = (t == nt - 2);
;             const char* a1 = cA + (size_t)(t + 1) * kstep;
;             const char* a2 = last ? nA : cA + (size_t)(t + 2) * kstep; const char* b2 = last ? nB : cB + (size_t)(t + 2) * kstep;
;             const char* a3 = a2 + kstep; const char* b3 = b2 + kstep;
;             PG8_LDB(B0, 0, 0); if (!HALFN) PG8_LDB(B1, 0, 1); PG8_SCHED; PG8_LDA(At, 0, 0); PG8_STAGE(PG8_SA(1, 1), a1 + hstep, voffA);
;             PG8_WAIT_V(8); PG8_WAIT_L(0); PG8_BAR; PG8_MMA(0, 0, At, B0); if (!HALFN) PG8_MMA(0, 1, At, B1); PG8_BAR; PG8_SCHED;
;             PG8_LDA(At, 0, 1); PG8_STAGE(PG8_SB(0, 0), b2, voffB); PG8_STAGE(PG8_SB(0, 1), b2 + bh1, voffB); PG8_STAGE(PG8_SA(0, 0), a2, voffA);
;             PG8_WAIT_V(8); PG8_WAIT_L(0); PG8_BAR; PG8_MMA(1, 0, At, B0); if (!HALFN) PG8_MMA(1, 1, At, B1); PG8_BAR; PG8_SCHED;
.LBB0_269:
	s_add_u32 s53, s8, 0xfffc0080
	s_addc_u32 s66, s9, -1
	s_add_i32 s82, 0, 0x10000
	s_cmp_eq_u32 s52, 12
	s_cselect_b32 s81, s5, s66
	s_cselect_b32 s80, s7, s53
	v_add_u32_e32 v18, s82, v1
	s_cselect_b32 s79, s39, s48
	s_cselect_b32 s78, s42, s47
	s_add_i32 s53, 0, 0x14000
	ds_read_b128 v[146:149], v18
	ds_read_b128 v[150:153], v18 offset:1024
	ds_read_b128 v[154:157], v18 offset:2048
	ds_read_b128 v[158:161], v18 offset:3072
	v_add_u32_e32 v18, s53, v1
	ds_read_b128 v[162:165], v18
	ds_read_b128 v[166:169], v18 offset:1024
	ds_read_b128 v[172:175], v18 offset:2048
	ds_read_b128 v[176:179], v18 offset:3072
	v_lshl_add_u64 v[196:197], s[8:9], 0, v[140:141]
	s_add_i32 m0, s67, 0xc000
	ds_read_b128 v[180:183], v170
	ds_read_b128 v[184:187], v170 offset:1024
	ds_read_b128 v[188:191], v170 offset:2048
	ds_read_b128 v[192:195], v170 offset:3072
	ds_read_b128 v[208:211], v170 offset:4096
	ds_read_b128 v[212:215], v170 offset:5120
	ds_read_b128 v[216:219], v170 offset:6144
	ds_read_b128 v[220:223], v170 offset:7168
	global_load_lds_dwordx4 v[196:197], off
	v_lshl_add_u64 v[196:197], s[8:9], 0, v[142:143]
	s_add_i32 m0, s67, 0xe000
	s_nop 0
	global_load_lds_dwordx4 v[196:197], off
	s_waitcnt vmcnt(8)
	s_waitcnt lgkmcnt(0)
	s_barrier
	s_setprio 1
	v_mfma_f32_16x16x32_bf16 v[128:131], v[146:149], v[180:183], v[128:131]
	v_mfma_f32_16x16x32_bf16 v[124:127], v[154:157], v[180:183], v[124:127]
	v_mfma_f32_16x16x32_bf16 v[112:115], v[146:149], v[188:191], v[112:115]
	v_mfma_f32_16x16x32_bf16 v[108:111], v[154:157], v[188:191], v[108:111]
	v_mfma_f32_16x16x32_bf16 v[96:99], v[146:149], v[208:211], v[96:99]
	v_mfma_f32_16x16x32_bf16 v[92:95], v[154:157], v[208:211], v[92:95]
	v_mfma_f32_16x16x32_bf16 v[80:83], v[146:149], v[216:219], v[80:83]
	v_mfma_f32_16x16x32_bf16 v[76:79], v[154:157], v[216:219], v[76:79]
	v_mfma_f32_16x16x32_bf16 v[128:131], v[150:153], v[184:187], v[128:131]
	v_mfma_f32_16x16x32_bf16 v[124:127], v[158:161], v[184:187], v[124:127]
	v_mfma_f32_16x16x32_bf16 v[112:115], v[150:153], v[192:195], v[112:115]
	v_mfma_f32_16x16x32_bf16 v[108:111], v[158:161], v[192:195], v[108:111]
	v_mfma_f32_16x16x32_bf16 v[96:99], v[150:153], v[212:215], v[96:99]
	v_mfma_f32_16x16x32_bf16 v[92:95], v[158:161], v[212:215], v[92:95]
	v_mfma_f32_16x16x32_bf16 v[80:83], v[150:153], v[220:223], v[80:83]
	v_mfma_f32_16x16x32_bf16 v[76:79], v[158:161], v[220:223], v[76:79]
	v_mfma_f32_16x16x32_bf16 v[120:123], v[162:165], v[180:183], v[120:123]
	v_mfma_f32_16x16x32_bf16 v[116:119], v[172:175], v[180:183], v[116:119]
	v_mfma_f32_16x16x32_bf16 v[104:107], v[162:165], v[188:191], v[104:107]
	v_mfma_f32_16x16x32_bf16 v[100:103], v[172:175], v[188:191], v[100:103]
	v_mfma_f32_16x16x32_bf16 v[88:91], v[162:165], v[208:211], v[88:91]
	v_mfma_f32_16x16x32_bf16 v[84:87], v[172:175], v[208:211], v[84:87]
	v_mfma_f32_16x16x32_bf16 v[72:75], v[162:165], v[216:219], v[72:75]
	v_mfma_f32_16x16x32_bf16 v[68:71], v[172:175], v[216:219], v[68:71]
	v_mfma_f32_16x16x32_bf16 v[120:123], v[166:169], v[184:187], v[120:123]
	v_mfma_f32_16x16x32_bf16 v[116:119], v[176:179], v[184:187], v[116:119]
	v_mfma_f32_16x16x32_bf16 v[104:107], v[166:169], v[192:195], v[104:107]
	v_mfma_f32_16x16x32_bf16 v[100:103], v[176:179], v[192:195], v[100:103]
	v_mfma_f32_16x16x32_bf16 v[88:91], v[166:169], v[212:215], v[88:91]
	v_mfma_f32_16x16x32_bf16 v[84:87], v[176:179], v[212:215], v[84:87]
	v_mfma_f32_16x16x32_bf16 v[72:75], v[166:169], v[220:223], v[72:75]
	v_mfma_f32_16x16x32_bf16 v[68:71], v[176:179], v[220:223], v[68:71]
	s_setprio 0
	s_barrier
	s_add_i32 s66, s82, s64
	v_lshl_add_u64 v[196:197], s[78:79], 0, v[134:135]
	s_mov_b32 m0, s66
	ds_read_b128 v[180:183], v170 offset:16384
	ds_read_b128 v[184:187], v170 offset:17408
	ds_read_b128 v[188:191], v170 offset:18432
	ds_read_b128 v[192:195], v170 offset:19456
	ds_read_b128 v[208:211], v170 offset:20480
	ds_read_b128 v[212:215], v170 offset:21504
	ds_read_b128 v[216:219], v170 offset:22528
	ds_read_b128 v[220:223], v170 offset:23552
	global_load_lds_dwordx4 v[196:197], off
	s_add_i32 m0, s66, 0x2000
	s_add_u32 s82, s78, 0x40000
	v_lshl_add_u64 v[224:225], s[78:79], 0, v[138:139]
	s_addc_u32 s83, s79, 0
	s_add_i32 s53, s53, s64
	global_load_lds_dwordx4 v[224:225], off
	v_lshl_add_u64 v[226:227], s[82:83], 0, v[134:135]
	s_mov_b32 m0, s53
	v_lshl_add_u64 v[228:229], s[80:81], 0, v[136:137]
	global_load_lds_dwordx4 v[226:227], off
	v_lshl_add_u64 v[226:227], s[82:83], 0, v[138:139]
	s_add_i32 m0, s53, 0x2000
	s_nop 0
	global_load_lds_dwordx4 v[226:227], off
	v_lshl_add_u64 v[226:227], s[80:81], 0, v[132:133]
	s_mov_b32 m0, s67
	s_nop 0
	global_load_lds_dwordx4 v[226:227], off
	s_mov_b32 m0, s70
	s_nop 0
	global_load_lds_dwordx4 v[228:229], off
	s_waitcnt vmcnt(8)
	s_waitcnt lgkmcnt(0)
	s_barrier
; #define PG8_STAGE(bufoff, gbase, voff) do { _Pragma("unroll") for (int _i = 0; _i < 2; ++_i) \
;         __builtin_amdgcn_global_load_lds((const unsigned*)((const char*)(gbase) + (voff)[_i]), (LAS unsigned*)(lds + (bufoff) + ldsw + _i * 8192), 16, 0, 0); } while (0)
; #define PG8_LDA(dst, b, h) do { _Pragma("unroll") for (int m = 0; m < 4; ++m) _Pragma("unroll") for (int k = 0; k < 2; ++k) dst[m][k] = *(const LAS bf16x8*)(lds + PG8_SA(b, h) + aoff + m * 2048 + k * 1024); } while (0)
; #define PG8_LDB(dst, b, h) do { _Pragma("unroll") for (int n = 0; n < 2; ++n) _Pragma("unroll") for (int k = 0; k < 2; ++k) dst[n][k] = *(const LAS bf16x8*)(lds + PG8_SB(b, h) + boff + n * 2048 + k * 1024); } while (0)
; #define PG8_MMA(ai, bj, At, Bt) do { __builtin_amdgcn_s_setprio(1); _Pragma("unroll") for (int m = 0; m < 4; ++m) _Pragma("unroll") for (int n = 0; n < 2; ++n) _Pragma("unroll") for (int k = 0; k < 2; ++k) \
;         acc[ai][bj][m][n] = __builtin_amdgcn_mfma_f32_16x16x32_bf16(Bt[n][k], At[m][k], acc[ai][bj][m][n], 0, 0, 0); __builtin_amdgcn_s_setprio(0); } while (0)
; #define PG8_WAIT_V(n) asm volatile("s_waitcnt vmcnt(" #n ")" ::: "memory")
; #define PG8_WAIT_L(n) asm volatile("s_waitcnt lgkmcnt(" #n ")" ::: "memory")
; #define PG8_BAR __builtin_amdgcn_s_barrier()
; #define PG8_SCHED __builtin_amdgcn_sched_barrier(0)
; template <class Epi, class Sched, bool HALFN = false>
; __device__ __forceinline__ void gemm_phase(LAS unsigned char* lds, const Gemm g, const Sched& S, const Epi& E, int wave_s) {
;     ...
;             PG8_LDA(At, 0, 1); PG8_STAGE(PG8_SB(0, 0), b2, voffB); PG8_STAGE(PG8_SB(0, 1), b2 + bh1, voffB); PG8_STAGE(PG8_SA(0, 0), a2, voffA);
;             PG8_WAIT_V(8); PG8_WAIT_L(0); PG8_BAR; PG8_MMA(1, 0, At, B0); if (!HALFN) PG8_MMA(1, 1, At, B1); PG8_BAR; PG8_SCHED;
;             PG8_LDB(B0, 1, 0); if (!HALFN) PG8_LDB(B1, 1, 1); PG8_SCHED; PG8_LDA(At, 1, 0); PG8_STAGE(PG8_SA(0, 1), a2 + hstep, voffA);
;             PG8_WAIT_V(8); PG8_WAIT_L(0); PG8_BAR; PG8_MMA(0, 0, At, B0); if (!HALFN) PG8_MMA(0, 1, At, B1); PG8_BAR; PG8_SCHED;
	s_setprio 1
	v_mfma_f32_16x16x32_bf16 v[64:67], v[146:149], v[180:183], v[64:67]
	v_mfma_f32_16x16x32_bf16 v[60:63], v[154:157], v[180:183], v[60:63]
	v_mfma_f32_16x16x32_bf16 v[48:51], v[146:149], v[188:191], v[48:51]
	v_mfma_f32_16x16x32_bf16 v[44:47], v[154:157], v[188:191], v[44:47]
	v_mfma_f32_16x16x32_bf16 v[32:35], v[146:149], v[208:211], v[32:35]
	v_mfma_f32_16x16x32_bf16 v[28:31], v[154:157], v[208:211], v[28:31]
	v_mfma_f32_16x16x32_bf16 v[14:17], v[146:149], v[216:219], v[14:17]
	v_mfma_f32_16x16x32_bf16 v[10:13], v[154:157], v[216:219], v[10:13]
	v_mfma_f32_16x16x32_bf16 v[64:67], v[150:153], v[184:187], v[64:67]
	v_mfma_f32_16x16x32_bf16 v[60:63], v[158:161], v[184:187], v[60:63]
	v_mfma_f32_16x16x32_bf16 v[48:51], v[150:153], v[192:195], v[48:51]
	v_mfma_f32_16x16x32_bf16 v[44:47], v[158:161], v[192:195], v[44:47]
	v_mfma_f32_16x16x32_bf16 v[32:35], v[150:153], v[212:215], v[32:35]
	v_mfma_f32_16x16x32_bf16 v[28:31], v[158:161], v[212:215], v[28:31]
	v_mfma_f32_16x16x32_bf16 v[14:17], v[150:153], v[220:223], v[14:17]
	v_mfma_f32_16x16x32_bf16 v[10:13], v[158:161], v[220:223], v[10:13]
	v_mfma_f32_16x16x32_bf16 v[56:59], v[162:165], v[180:183], v[56:59]
	v_mfma_f32_16x16x32_bf16 v[52:55], v[172:175], v[180:183], v[52:55]
	v_mfma_f32_16x16x32_bf16 v[40:43], v[162:165], v[188:191], v[40:43]
	v_mfma_f32_16x16x32_bf16 v[36:39], v[172:175], v[188:191], v[36:39]
	v_mfma_f32_16x16x32_bf16 v[24:27], v[162:165], v[208:211], v[24:27]
	v_mfma_f32_16x16x32_bf16 v[20:23], v[172:175], v[208:211], v[20:23]
	v_mfma_f32_16x16x32_bf16 v[6:9], v[162:165], v[216:219], v[6:9]
	v_mfma_f32_16x16x32_bf16 v[2:5], v[172:175], v[216:219], v[2:5]
	v_mfma_f32_16x16x32_bf16 v[56:59], v[166:169], v[184:187], v[56:59]
	v_mfma_f32_16x16x32_bf16 v[52:55], v[176:179], v[184:187], v[52:55]
	v_mfma_f32_16x16x32_bf16 v[40:43], v[166:169], v[192:195], v[40:43]
	v_mfma_f32_16x16x32_bf16 v[36:39], v[176:179], v[192:195], v[36:39]
	v_mfma_f32_16x16x32_bf16 v[24:27], v[166:169], v[212:215], v[24:27]
	v_mfma_f32_16x16x32_bf16 v[20:23], v[176:179], v[212:215], v[20:23]
	v_mfma_f32_16x16x32_bf16 v[6:9], v[166:169], v[220:223], v[6:9]
	v_mfma_f32_16x16x32_bf16 v[2:5], v[176:179], v[220:223], v[2:5]
	s_setprio 0
	s_barrier
	s_add_i32 s53, 0, 0x18000
	v_add_u32_e32 v18, s53, v1
	s_add_i32 s66, 0, 0x1c000
	ds_read_b128 v[146:149], v18
	ds_read_b128 v[150:153], v18 offset:1024
	ds_read_b128 v[154:157], v18 offset:2048
	ds_read_b128 v[158:161], v18 offset:3072
	v_add_u32_e32 v18, s66, v1
	ds_read_b128 v[162:165], v18
	ds_read_b128 v[166:169], v18 offset:1024
	ds_read_b128 v[172:175], v18 offset:2048
	ds_read_b128 v[176:179], v18 offset:3072
	s_add_u32 s80, s80, 0x40000
	s_addc_u32 s81, s81, 0
	s_mov_b32 m0, s71
	v_lshl_add_u64 v[230:231], s[80:81], 0, v[132:133]
	ds_read_b128 v[180:183], v170 offset:32768
	ds_read_b128 v[184:187], v170 offset:33792
	ds_read_b128 v[188:191], v170 offset:34816
	ds_read_b128 v[192:195], v170 offset:35840
	ds_read_b128 v[208:211], v170 offset:36864
	ds_read_b128 v[212:215], v170 offset:37888
	ds_read_b128 v[216:219], v170 offset:38912
	ds_read_b128 v[220:223], v170 offset:39936
	global_load_lds_dwordx4 v[230:231], off
	v_lshl_add_u64 v[230:231], s[80:81], 0, v[136:137]
	s_mov_b32 m0, s74
	s_nop 0
	global_load_lds_dwordx4 v[230:231], off
	s_waitcnt vmcnt(8)
	s_waitcnt lgkmcnt(0)
	s_barrier
	s_setprio 1
	v_mfma_f32_16x16x32_bf16 v[128:131], v[146:149], v[180:183], v[128:131]
	v_mfma_f32_16x16x32_bf16 v[124:127], v[154:157], v[180:183], v[124:127]
	v_mfma_f32_16x16x32_bf16 v[112:115], v[146:149], v[188:191], v[112:115]
	v_mfma_f32_16x16x32_bf16 v[108:111], v[154:157], v[188:191], v[108:111]
	v_mfma_f32_16x16x32_bf16 v[96:99], v[146:149], v[208:211], v[96:99]
	v_mfma_f32_16x16x32_bf16 v[92:95], v[154:157], v[208:211], v[92:95]
	v_mfma_f32_16x16x32_bf16 v[80:83], v[146:149], v[216:219], v[80:83]
	v_mfma_f32_16x16x32_bf16 v[76:79], v[154:157], v[216:219], v[76:79]
	v_mfma_f32_16x16x32_bf16 v[128:131], v[150:153], v[184:187], v[128:131]
	v_mfma_f32_16x16x32_bf16 v[124:127], v[158:161], v[184:187], v[124:127]
	v_mfma_f32_16x16x32_bf16 v[112:115], v[150:153], v[192:195], v[112:115]
	v_mfma_f32_16x16x32_bf16 v[108:111], v[158:161], v[192:195], v[108:111]
	v_mfma_f32_16x16x32_bf16 v[96:99], v[150:153], v[212:215], v[96:99]
	v_mfma_f32_16x16x32_bf16 v[92:95], v[158:161], v[212:215], v[92:95]
	v_mfma_f32_16x16x32_bf16 v[80:83], v[150:153], v[220:223], v[80:83]
	v_mfma_f32_16x16x32_bf16 v[76:79], v[158:161], v[220:223], v[76:79]
	v_mfma_f32_16x16x32_bf16 v[120:123], v[162:165], v[180:183], v[120:123]
	v_mfma_f32_16x16x32_bf16 v[116:119], v[172:175], v[180:183], v[116:119]
	v_mfma_f32_16x16x32_bf16 v[104:107], v[162:165], v[188:191], v[104:107]
	v_mfma_f32_16x16x32_bf16 v[100:103], v[172:175], v[188:191], v[100:103]
	v_mfma_f32_16x16x32_bf16 v[88:91], v[162:165], v[208:211], v[88:91]
	v_mfma_f32_16x16x32_bf16 v[84:87], v[172:175], v[208:211], v[84:87]
	v_mfma_f32_16x16x32_bf16 v[72:75], v[162:165], v[216:219], v[72:75]
	v_mfma_f32_16x16x32_bf16 v[68:71], v[172:175], v[216:219], v[68:71]
	v_mfma_f32_16x16x32_bf16 v[120:123], v[166:169], v[184:187], v[120:123]
	v_mfma_f32_16x16x32_bf16 v[116:119], v[176:179], v[184:187], v[116:119]
	v_mfma_f32_16x16x32_bf16 v[104:107], v[166:169], v[192:195], v[104:107]
	v_mfma_f32_16x16x32_bf16 v[100:103], v[176:179], v[192:195], v[100:103]
	v_mfma_f32_16x16x32_bf16 v[88:91], v[166:169], v[212:215], v[88:91]
	v_mfma_f32_16x16x32_bf16 v[84:87], v[176:179], v[212:215], v[84:87]
	v_mfma_f32_16x16x32_bf16 v[72:75], v[166:169], v[220:223], v[72:75]
	v_mfma_f32_16x16x32_bf16 v[68:71], v[176:179], v[220:223], v[68:71]
	s_setprio 0
	s_barrier
; #define PG8_STAGE(bufoff, gbase, voff) do { _Pragma("unroll") for (int _i = 0; _i < 2; ++_i) \
;         __builtin_amdgcn_global_load_lds((const unsigned*)((const char*)(gbase) + (voff)[_i]), (LAS unsigned*)(lds + (bufoff) + ldsw + _i * 8192), 16, 0, 0); } while (0)
; #define PG8_LDA(dst, b, h) do { _Pragma("unroll") for (int m = 0; m < 4; ++m) _Pragma("unroll") for (int k = 0; k < 2; ++k) dst[m][k] = *(const LAS bf16x8*)(lds + PG8_SA(b, h) + aoff + m * 2048 + k * 1024); } while (0)
; #define PG8_MMA(ai, bj, At, Bt) do { __builtin_amdgcn_s_setprio(1); _Pragma("unroll") for (int m = 0; m < 4; ++m) _Pragma("unroll") for (int n = 0; n < 2; ++n) _Pragma("unroll") for (int k = 0; k < 2; ++k) \
;         acc[ai][bj][m][n] = __builtin_amdgcn_mfma_f32_16x16x32_bf16(Bt[n][k], At[m][k], acc[ai][bj][m][n], 0, 0, 0); __builtin_amdgcn_s_setprio(0); } while (0)
; #define PG8_WAIT_V(n) asm volatile("s_waitcnt vmcnt(" #n ")" ::: "memory")
; #define PG8_WAIT_L(n) asm volatile("s_waitcnt lgkmcnt(" #n ")" ::: "memory")
; #define PG8_BAR __builtin_amdgcn_s_barrier()
; #define PG8_SCHED __builtin_amdgcn_sched_barrier(0)
; template <class Epi, class Sched, bool HALFN = false>
; __device__ __forceinline__ void gemm_phase(LAS unsigned char* lds, const Gemm g, const Sched& S, const Epi& E, int wave_s) {
;     ...
;             PG8_LDA(At, 1, 1); PG8_STAGE(PG8_SB(1, 0), b3, voffB); PG8_STAGE(PG8_SB(1, 1), b3 + bh1, voffB); PG8_STAGE(PG8_SA(1, 0), a3, voffA);
;             PG8_WAIT_V(8); PG8_WAIT_L(0); PG8_BAR; PG8_MMA(1, 0, At, B0); if (!HALFN) PG8_MMA(1, 1, At, B1); PG8_BAR; PG8_SCHED;
;         }
	s_add_i32 s53, s53, s64
	v_lshl_add_u64 v[196:197], v[196:197], 0, s[50:51]
	s_mov_b32 m0, s53
	ds_read_b128 v[180:183], v170 offset:49152
	ds_read_b128 v[184:187], v170 offset:50176
	ds_read_b128 v[188:191], v170 offset:51200
	ds_read_b128 v[192:195], v170 offset:52224
	ds_read_b128 v[208:211], v170 offset:53248
	ds_read_b128 v[212:215], v170 offset:54272
	ds_read_b128 v[216:219], v170 offset:55296
	ds_read_b128 v[220:223], v170 offset:56320
	global_load_lds_dwordx4 v[196:197], off
	s_add_i32 m0, s53, 0x2000
	s_add_u32 s78, s78, 0x40080
	v_lshl_add_u64 v[196:197], v[224:225], 0, s[50:51]
	s_addc_u32 s79, s79, 0
	s_add_i32 s53, s66, s64
	global_load_lds_dwordx4 v[196:197], off
	v_lshl_add_u64 v[196:197], s[78:79], 0, v[134:135]
	s_mov_b32 m0, s53
	s_nop 0
	global_load_lds_dwordx4 v[196:197], off
	v_lshl_add_u64 v[196:197], s[78:79], 0, v[138:139]
	s_add_i32 m0, s53, 0x2000
	s_nop 0
	global_load_lds_dwordx4 v[196:197], off
	v_lshl_add_u64 v[196:197], v[226:227], 0, s[50:51]
	s_mov_b32 m0, s75
	s_nop 0
	global_load_lds_dwordx4 v[196:197], off
	v_lshl_add_u64 v[196:197], v[228:229], 0, s[50:51]
	s_mov_b32 m0, s88
	s_nop 0
	global_load_lds_dwordx4 v[196:197], off
	s_waitcnt vmcnt(8)
	s_waitcnt lgkmcnt(0)
	s_barrier
	s_setprio 1
	v_mfma_f32_16x16x32_bf16 v[64:67], v[146:149], v[180:183], v[64:67]
	v_mfma_f32_16x16x32_bf16 v[60:63], v[154:157], v[180:183], v[60:63]
	v_mfma_f32_16x16x32_bf16 v[48:51], v[146:149], v[188:191], v[48:51]
	v_mfma_f32_16x16x32_bf16 v[44:47], v[154:157], v[188:191], v[44:47]
	v_mfma_f32_16x16x32_bf16 v[32:35], v[146:149], v[208:211], v[32:35]
	v_mfma_f32_16x16x32_bf16 v[28:31], v[154:157], v[208:211], v[28:31]
	v_mfma_f32_16x16x32_bf16 v[14:17], v[146:149], v[216:219], v[14:17]
	v_mfma_f32_16x16x32_bf16 v[10:13], v[154:157], v[216:219], v[10:13]
	v_mfma_f32_16x16x32_bf16 v[64:67], v[150:153], v[184:187], v[64:67]
	v_mfma_f32_16x16x32_bf16 v[60:63], v[158:161], v[184:187], v[60:63]
	v_mfma_f32_16x16x32_bf16 v[48:51], v[150:153], v[192:195], v[48:51]
	v_mfma_f32_16x16x32_bf16 v[44:47], v[158:161], v[192:195], v[44:47]
	v_mfma_f32_16x16x32_bf16 v[32:35], v[150:153], v[212:215], v[32:35]
	v_mfma_f32_16x16x32_bf16 v[28:31], v[158:161], v[212:215], v[28:31]
	v_mfma_f32_16x16x32_bf16 v[14:17], v[150:153], v[220:223], v[14:17]
	v_mfma_f32_16x16x32_bf16 v[10:13], v[158:161], v[220:223], v[10:13]
	v_mfma_f32_16x16x32_bf16 v[56:59], v[162:165], v[180:183], v[56:59]
	v_mfma_f32_16x16x32_bf16 v[52:55], v[172:175], v[180:183], v[52:55]
	v_mfma_f32_16x16x32_bf16 v[40:43], v[162:165], v[188:191], v[40:43]
	v_mfma_f32_16x16x32_bf16 v[36:39], v[172:175], v[188:191], v[36:39]
	v_mfma_f32_16x16x32_bf16 v[24:27], v[162:165], v[208:211], v[24:27]
	v_mfma_f32_16x16x32_bf16 v[20:23], v[172:175], v[208:211], v[20:23]
	v_mfma_f32_16x16x32_bf16 v[6:9], v[162:165], v[216:219], v[6:9]
	v_mfma_f32_16x16x32_bf16 v[2:5], v[172:175], v[216:219], v[2:5]
	v_mfma_f32_16x16x32_bf16 v[56:59], v[166:169], v[184:187], v[56:59]
	v_mfma_f32_16x16x32_bf16 v[52:55], v[176:179], v[184:187], v[52:55]
	v_mfma_f32_16x16x32_bf16 v[40:43], v[166:169], v[192:195], v[40:43]
	v_mfma_f32_16x16x32_bf16 v[36:39], v[176:179], v[192:195], v[36:39]
	v_mfma_f32_16x16x32_bf16 v[24:27], v[166:169], v[212:215], v[24:27]
	v_mfma_f32_16x16x32_bf16 v[20:23], v[176:179], v[212:215], v[20:23]
	v_mfma_f32_16x16x32_bf16 v[6:9], v[166:169], v[220:223], v[6:9]
	v_mfma_f32_16x16x32_bf16 v[2:5], v[176:179], v[220:223], v[2:5]
	s_setprio 0
	s_add_i32 s52, s52, 2
	s_add_u32 s8, s8, 0x100
	s_addc_u32 s9, s9, 0
	s_add_u32 s47, s47, 0x100
	s_addc_u32 s48, s48, 0
	s_cmp_gt_u32 s52, 13
	s_barrier
	s_cbranch_scc0 .LBB0_269
	s_and_b64 vcc, exec, s[26:27]
	s_cbranch_vccz .LBB0_272
	s_barrier

; #define PG8_STAGE(bufoff, gbase, voff) do { _Pragma("unroll") for (int _i = 0; _i < 2; ++_i) \
;         __builtin_amdgcn_global_load_lds((const unsigned*)((const char*)(gbase) + (voff)[_i]), (LAS unsigned*)(lds + (bufoff) + ldsw + _i * 8192), 16, 0, 0); } while (0)
; #define PG8_LDA(dst, b, h) do { _Pragma("unroll") for (int m = 0; m < 4; ++m) _Pragma("unroll") for (int k = 0; k < 2; ++k) dst[m][k] = *(const LAS bf16x8*)(lds + PG8_SA(b, h) + aoff + m * 2048 + k * 1024); } while (0)
; #define PG8_LDB(dst, b, h) do { _Pragma("unroll") for (int n = 0; n < 2; ++n) _Pragma("unroll") for (int k = 0; k < 2; ++k) dst[n][k] = *(const LAS bf16x8*)(lds + PG8_SB(b, h) + boff + n * 2048 + k * 1024); } while (0)
; #define PG8_WAIT_V(n) asm volatile("s_waitcnt vmcnt(" #n ")" ::: "memory")
; #define PG8_WAIT_L(n) asm volatile("s_waitcnt lgkmcnt(" #n ")" ::: "memory")
; #define PG8_BAR __builtin_amdgcn_s_barrier()
; #define PG8_SCHED __builtin_amdgcn_sched_barrier(0)
; template <class Epi, class Sched, bool HALFN = false>
; __device__ __forceinline__ void gemm_phase(LAS unsigned char* lds, const Gemm g, const Sched& S, const Epi& E, int wave_s) {
;     ...
;         const bool has_next = S.next(ui + 1, nxt);
;         const char* nA = has_next ? (const char*)g.A + (size_t)nxt.z * g.zA * 2 + (size_t)nxt.pm * tstep : cA; const char* nB = has_next ? (const char*)g.Bt + (size_t)nxt.z * g.zB * 2 + (size_t)nxt.pn * (HALFN ? hstep : tstep) : cB;
;         for (int t = 0; t < nt; t += 2) {
;             const bool last = (t == nt - 2);
;             const char* a1 = cA + (size_t)(t + 1) * kstep;
;             const char* a2 = last ? nA : cA + (size_t)(t + 2) * kstep; const char* b2 = last ? nB : cB + (size_t)(t + 2) * kstep;
;             const char* a3 = a2 + kstep; const char* b3 = b2 + kstep;
;             PG8_LDB(B0, 0, 0); if (!HALFN) PG8_LDB(B1, 0, 1); PG8_SCHED; PG8_LDA(At, 0, 0); PG8_STAGE(PG8_SA(1, 1), a1 + hstep, voffA);
;             PG8_WAIT_V(8); PG8_WAIT_L(0); PG8_BAR; PG8_MMA(0, 0, At, B0); if (!HALFN) PG8_MMA(0, 1, At, B1); PG8_BAR; PG8_SCHED;
;             PG8_LDA(At, 0, 1); PG8_STAGE(PG8_SB(0, 0), b2, voffB); PG8_STAGE(PG8_SB(0, 1), b2 + bh1, voffB); PG8_STAGE(PG8_SA(0, 0), a2, voffA);
;             PG8_WAIT_V(8); PG8_WAIT_L(0); PG8_BAR; PG8_MMA(1, 0, At, B0); if (!HALFN) PG8_MMA(1, 1, At, B1); PG8_BAR; PG8_SCHED;
.LBB0_985:
	s_add_u32 s34, s6, 0xfffc0080
	s_addc_u32 s35, s7, -1
	s_add_i32 s53, 0, 0x10000
	s_cmp_eq_u32 s52, 12
	s_cselect_b32 s37, s5, s35
	s_cselect_b32 s36, s25, s34
	v_add_u32_e32 v18, s53, v1
	s_cselect_b32 s35, s23, s48
	s_cselect_b32 s34, s31, s42
	s_add_i32 s66, 0, 0x14000
	ds_read_b128 v[132:135], v18
	ds_read_b128 v[136:139], v18 offset:1024
	ds_read_b128 v[140:143], v18 offset:2048
	ds_read_b128 v[144:147], v18 offset:3072
	v_add_u32_e32 v18, s66, v1
	ds_read_b128 v[148:151], v18
	ds_read_b128 v[152:155], v18 offset:1024
	ds_read_b128 v[156:159], v18 offset:2048
	ds_read_b128 v[160:163], v18 offset:3072
	v_lshl_add_u64 v[198:199], s[6:7], 0, v[172:173]
	s_add_i32 m0, s45, 0xc000
	ds_read_b128 v[176:179], v184
	ds_read_b128 v[180:183], v184 offset:1024
	ds_read_b128 v[186:189], v184 offset:2048
	ds_read_b128 v[190:193], v184 offset:3072
	ds_read_b128 v[194:197], v184 offset:4096
	ds_read_b128 v[208:211], v184 offset:5120
	ds_read_b128 v[212:215], v184 offset:6144
	ds_read_b128 v[216:219], v184 offset:7168
	global_load_lds_dwordx4 v[198:199], off
	v_lshl_add_u64 v[198:199], s[6:7], 0, v[174:175]
	s_add_i32 m0, s45, 0xe000
	s_nop 0
	global_load_lds_dwordx4 v[198:199], off
	s_waitcnt vmcnt(8)
	s_waitcnt lgkmcnt(0)
	s_barrier
	s_setprio 1
	v_mfma_f32_16x16x32_bf16 v[128:131], v[132:135], v[176:179], v[128:131]
	v_mfma_f32_16x16x32_bf16 v[124:127], v[140:143], v[176:179], v[124:127]
	v_mfma_f32_16x16x32_bf16 v[112:115], v[132:135], v[186:189], v[112:115]
	v_mfma_f32_16x16x32_bf16 v[108:111], v[140:143], v[186:189], v[108:111]
	v_mfma_f32_16x16x32_bf16 v[96:99], v[132:135], v[194:197], v[96:99]
	v_mfma_f32_16x16x32_bf16 v[92:95], v[140:143], v[194:197], v[92:95]
	v_mfma_f32_16x16x32_bf16 v[80:83], v[132:135], v[212:215], v[80:83]
	v_mfma_f32_16x16x32_bf16 v[76:79], v[140:143], v[212:215], v[76:79]
	v_mfma_f32_16x16x32_bf16 v[128:131], v[136:139], v[180:183], v[128:131]
	v_mfma_f32_16x16x32_bf16 v[124:127], v[144:147], v[180:183], v[124:127]
	v_mfma_f32_16x16x32_bf16 v[112:115], v[136:139], v[190:193], v[112:115]
	v_mfma_f32_16x16x32_bf16 v[108:111], v[144:147], v[190:193], v[108:111]
	v_mfma_f32_16x16x32_bf16 v[96:99], v[136:139], v[208:211], v[96:99]
	v_mfma_f32_16x16x32_bf16 v[92:95], v[144:147], v[208:211], v[92:95]
	v_mfma_f32_16x16x32_bf16 v[80:83], v[136:139], v[216:219], v[80:83]
	v_mfma_f32_16x16x32_bf16 v[76:79], v[144:147], v[216:219], v[76:79]
	s_setprio 0
	s_setprio 1
	v_mfma_f32_16x16x32_bf16 v[120:123], v[148:151], v[176:179], v[120:123]
	v_mfma_f32_16x16x32_bf16 v[116:119], v[156:159], v[176:179], v[116:119]
	v_mfma_f32_16x16x32_bf16 v[104:107], v[148:151], v[186:189], v[104:107]
	v_mfma_f32_16x16x32_bf16 v[100:103], v[156:159], v[186:189], v[100:103]
	v_mfma_f32_16x16x32_bf16 v[88:91], v[148:151], v[194:197], v[88:91]
	v_mfma_f32_16x16x32_bf16 v[84:87], v[156:159], v[194:197], v[84:87]
	v_mfma_f32_16x16x32_bf16 v[72:75], v[148:151], v[212:215], v[72:75]
	v_mfma_f32_16x16x32_bf16 v[68:71], v[156:159], v[212:215], v[68:71]
	v_mfma_f32_16x16x32_bf16 v[120:123], v[152:155], v[180:183], v[120:123]
	v_mfma_f32_16x16x32_bf16 v[116:119], v[160:163], v[180:183], v[116:119]
	v_mfma_f32_16x16x32_bf16 v[104:107], v[152:155], v[190:193], v[104:107]
	v_mfma_f32_16x16x32_bf16 v[100:103], v[160:163], v[190:193], v[100:103]
	v_mfma_f32_16x16x32_bf16 v[88:91], v[152:155], v[208:211], v[88:91]
	v_mfma_f32_16x16x32_bf16 v[84:87], v[160:163], v[208:211], v[84:87]
	v_mfma_f32_16x16x32_bf16 v[72:75], v[152:155], v[216:219], v[72:75]
	v_mfma_f32_16x16x32_bf16 v[68:71], v[160:163], v[216:219], v[68:71]
	s_setprio 0
	s_barrier
	s_add_i32 s53, s53, s41
	v_lshl_add_u64 v[198:199], s[34:35], 0, v[166:167]
	s_mov_b32 m0, s53
	ds_read_b128 v[176:179], v184 offset:16384
	ds_read_b128 v[180:183], v184 offset:17408
	ds_read_b128 v[186:189], v184 offset:18432
	ds_read_b128 v[190:193], v184 offset:19456
	ds_read_b128 v[194:197], v184 offset:20480
	ds_read_b128 v[208:211], v184 offset:21504
	ds_read_b128 v[212:215], v184 offset:22528
	ds_read_b128 v[216:219], v184 offset:23552
	global_load_lds_dwordx4 v[198:199], off
	s_add_i32 m0, s53, 0x2000
	s_add_u32 s76, s34, 0x40000
	v_lshl_add_u64 v[202:203], s[34:35], 0, v[170:171]
	s_addc_u32 s77, s35, 0
	s_add_i32 s53, s66, s41
	global_load_lds_dwordx4 v[202:203], off
	v_lshl_add_u64 v[220:221], s[76:77], 0, v[166:167]
	s_mov_b32 m0, s53
	v_lshl_add_u64 v[222:223], s[36:37], 0, v[168:169]
	global_load_lds_dwordx4 v[220:221], off
	v_lshl_add_u64 v[220:221], s[76:77], 0, v[170:171]
	s_add_i32 m0, s53, 0x2000
	s_nop 0
	global_load_lds_dwordx4 v[220:221], off
	v_lshl_add_u64 v[220:221], s[36:37], 0, v[164:165]
	s_mov_b32 m0, s45
	s_nop 0
	global_load_lds_dwordx4 v[220:221], off
	s_mov_b32 m0, s46
	s_nop 0
	global_load_lds_dwordx4 v[222:223], off
	s_waitcnt vmcnt(8)
	s_waitcnt lgkmcnt(0)
	s_barrier
; #define PG8_STAGE(bufoff, gbase, voff) do { _Pragma("unroll") for (int _i = 0; _i < 2; ++_i) \
;         __builtin_amdgcn_global_load_lds((const unsigned*)((const char*)(gbase) + (voff)[_i]), (LAS unsigned*)(lds + (bufoff) + ldsw + _i * 8192), 16, 0, 0); } while (0)
; #define PG8_LDA(dst, b, h) do { _Pragma("unroll") for (int m = 0; m < 4; ++m) _Pragma("unroll") for (int k = 0; k < 2; ++k) dst[m][k] = *(const LAS bf16x8*)(lds + PG8_SA(b, h) + aoff + m * 2048 + k * 1024); } while (0)
; #define PG8_LDB(dst, b, h) do { _Pragma("unroll") for (int n = 0; n < 2; ++n) _Pragma("unroll") for (int k = 0; k < 2; ++k) dst[n][k] = *(const LAS bf16x8*)(lds + PG8_SB(b, h) + boff + n * 2048 + k * 1024); } while (0)
; #define PG8_MMA(ai, bj, At, Bt) do { __builtin_amdgcn_s_setprio(1); _Pragma("unroll") for (int m = 0; m < 4; ++m) _Pragma("unroll") for (int n = 0; n < 2; ++n) _Pragma("unroll") for (int k = 0; k < 2; ++k) \
;         acc[ai][bj][m][n] = __builtin_amdgcn_mfma_f32_16x16x32_bf16(Bt[n][k], At[m][k], acc[ai][bj][m][n], 0, 0, 0); __builtin_amdgcn_s_setprio(0); } while (0)
; #define PG8_WAIT_V(n) asm volatile("s_waitcnt vmcnt(" #n ")" ::: "memory")
; #define PG8_WAIT_L(n) asm volatile("s_waitcnt lgkmcnt(" #n ")" ::: "memory")
; #define PG8_BAR __builtin_amdgcn_s_barrier()
; #define PG8_SCHED __builtin_amdgcn_sched_barrier(0)
; template <class Epi, class Sched, bool HALFN = false>
; __device__ __forceinline__ void gemm_phase(LAS unsigned char* lds, const Gemm g, const Sched& S, const Epi& E, int wave_s) {
;     ...
;             PG8_LDA(At, 0, 1); PG8_STAGE(PG8_SB(0, 0), b2, voffB); PG8_STAGE(PG8_SB(0, 1), b2 + bh1, voffB); PG8_STAGE(PG8_SA(0, 0), a2, voffA);
;             PG8_WAIT_V(8); PG8_WAIT_L(0); PG8_BAR; PG8_MMA(1, 0, At, B0); if (!HALFN) PG8_MMA(1, 1, At, B1); PG8_BAR; PG8_SCHED;
;             PG8_LDB(B0, 1, 0); if (!HALFN) PG8_LDB(B1, 1, 1); PG8_SCHED; PG8_LDA(At, 1, 0); PG8_STAGE(PG8_SA(0, 1), a2 + hstep, voffA);
;             PG8_WAIT_V(8); PG8_WAIT_L(0); PG8_BAR; PG8_MMA(0, 0, At, B0); if (!HALFN) PG8_MMA(0, 1, At, B1); PG8_BAR; PG8_SCHED;
	s_setprio 1
	v_mfma_f32_16x16x32_bf16 v[64:67], v[132:135], v[176:179], v[64:67]
	v_mfma_f32_16x16x32_bf16 v[60:63], v[140:143], v[176:179], v[60:63]
	v_mfma_f32_16x16x32_bf16 v[48:51], v[132:135], v[186:189], v[48:51]
	v_mfma_f32_16x16x32_bf16 v[44:47], v[140:143], v[186:189], v[44:47]
	v_mfma_f32_16x16x32_bf16 v[32:35], v[132:135], v[194:197], v[32:35]
	v_mfma_f32_16x16x32_bf16 v[28:31], v[140:143], v[194:197], v[28:31]
	v_mfma_f32_16x16x32_bf16 v[14:17], v[132:135], v[212:215], v[14:17]
	v_mfma_f32_16x16x32_bf16 v[10:13], v[140:143], v[212:215], v[10:13]
	v_mfma_f32_16x16x32_bf16 v[64:67], v[136:139], v[180:183], v[64:67]
	v_mfma_f32_16x16x32_bf16 v[60:63], v[144:147], v[180:183], v[60:63]
	v_mfma_f32_16x16x32_bf16 v[48:51], v[136:139], v[190:193], v[48:51]
	v_mfma_f32_16x16x32_bf16 v[44:47], v[144:147], v[190:193], v[44:47]
	v_mfma_f32_16x16x32_bf16 v[32:35], v[136:139], v[208:211], v[32:35]
	v_mfma_f32_16x16x32_bf16 v[28:31], v[144:147], v[208:211], v[28:31]
	v_mfma_f32_16x16x32_bf16 v[14:17], v[136:139], v[216:219], v[14:17]
	v_mfma_f32_16x16x32_bf16 v[10:13], v[144:147], v[216:219], v[10:13]
	s_setprio 0
	s_setprio 1
	v_mfma_f32_16x16x32_bf16 v[56:59], v[148:151], v[176:179], v[56:59]
	v_mfma_f32_16x16x32_bf16 v[52:55], v[156:159], v[176:179], v[52:55]
	v_mfma_f32_16x16x32_bf16 v[40:43], v[148:151], v[186:189], v[40:43]
	v_mfma_f32_16x16x32_bf16 v[36:39], v[156:159], v[186:189], v[36:39]
	v_mfma_f32_16x16x32_bf16 v[24:27], v[148:151], v[194:197], v[24:27]
	v_mfma_f32_16x16x32_bf16 v[20:23], v[156:159], v[194:197], v[20:23]
	v_mfma_f32_16x16x32_bf16 v[6:9], v[148:151], v[212:215], v[6:9]
	v_mfma_f32_16x16x32_bf16 v[2:5], v[156:159], v[212:215], v[2:5]
	v_mfma_f32_16x16x32_bf16 v[56:59], v[152:155], v[180:183], v[56:59]
	v_mfma_f32_16x16x32_bf16 v[52:55], v[160:163], v[180:183], v[52:55]
	v_mfma_f32_16x16x32_bf16 v[40:43], v[152:155], v[190:193], v[40:43]
	v_mfma_f32_16x16x32_bf16 v[36:39], v[160:163], v[190:193], v[36:39]
	v_mfma_f32_16x16x32_bf16 v[24:27], v[152:155], v[208:211], v[24:27]
	v_mfma_f32_16x16x32_bf16 v[20:23], v[160:163], v[208:211], v[20:23]
	v_mfma_f32_16x16x32_bf16 v[6:9], v[152:155], v[216:219], v[6:9]
	v_mfma_f32_16x16x32_bf16 v[2:5], v[160:163], v[216:219], v[2:5]
	s_setprio 0
	s_barrier
	s_add_i32 s53, 0, 0x18000
	v_add_u32_e32 v18, s53, v1
	s_add_i32 s66, 0, 0x1c000
	ds_read_b128 v[132:135], v18
	ds_read_b128 v[136:139], v18 offset:1024
	ds_read_b128 v[140:143], v18 offset:2048
	ds_read_b128 v[144:147], v18 offset:3072
	v_add_u32_e32 v18, s66, v1
	ds_read_b128 v[148:151], v18
	ds_read_b128 v[152:155], v18 offset:1024
	ds_read_b128 v[156:159], v18 offset:2048
	ds_read_b128 v[160:163], v18 offset:3072
	s_add_u32 s36, s36, 0x40000
	s_addc_u32 s37, s37, 0
	s_mov_b32 m0, s47
	v_lshl_add_u64 v[224:225], s[36:37], 0, v[164:165]
	ds_read_b128 v[176:179], v184 offset:32768
	ds_read_b128 v[180:183], v184 offset:33792
	ds_read_b128 v[186:189], v184 offset:34816
	ds_read_b128 v[190:193], v184 offset:35840
	ds_read_b128 v[194:197], v184 offset:36864
	ds_read_b128 v[208:211], v184 offset:37888
	ds_read_b128 v[212:215], v184 offset:38912
	ds_read_b128 v[216:219], v184 offset:39936
	global_load_lds_dwordx4 v[224:225], off
	v_lshl_add_u64 v[224:225], s[36:37], 0, v[168:169]
	s_mov_b32 m0, s55
	s_nop 0
	global_load_lds_dwordx4 v[224:225], off
	s_waitcnt vmcnt(8)
	s_waitcnt lgkmcnt(0)
	s_barrier
	s_setprio 1
	v_mfma_f32_16x16x32_bf16 v[128:131], v[132:135], v[176:179], v[128:131]
	v_mfma_f32_16x16x32_bf16 v[124:127], v[140:143], v[176:179], v[124:127]
	v_mfma_f32_16x16x32_bf16 v[112:115], v[132:135], v[186:189], v[112:115]
	v_mfma_f32_16x16x32_bf16 v[108:111], v[140:143], v[186:189], v[108:111]
	v_mfma_f32_16x16x32_bf16 v[96:99], v[132:135], v[194:197], v[96:99]
	v_mfma_f32_16x16x32_bf16 v[92:95], v[140:143], v[194:197], v[92:95]
	v_mfma_f32_16x16x32_bf16 v[80:83], v[132:135], v[212:215], v[80:83]
	v_mfma_f32_16x16x32_bf16 v[76:79], v[140:143], v[212:215], v[76:79]
	v_mfma_f32_16x16x32_bf16 v[128:131], v[136:139], v[180:183], v[128:131]
	v_mfma_f32_16x16x32_bf16 v[124:127], v[144:147], v[180:183], v[124:127]
	v_mfma_f32_16x16x32_bf16 v[112:115], v[136:139], v[190:193], v[112:115]
	v_mfma_f32_16x16x32_bf16 v[108:111], v[144:147], v[190:193], v[108:111]
	v_mfma_f32_16x16x32_bf16 v[96:99], v[136:139], v[208:211], v[96:99]
	v_mfma_f32_16x16x32_bf16 v[92:95], v[144:147], v[208:211], v[92:95]
	v_mfma_f32_16x16x32_bf16 v[80:83], v[136:139], v[216:219], v[80:83]
	v_mfma_f32_16x16x32_bf16 v[76:79], v[144:147], v[216:219], v[76:79]
	s_setprio 0
	s_setprio 1
	v_mfma_f32_16x16x32_bf16 v[120:123], v[148:151], v[176:179], v[120:123]
	v_mfma_f32_16x16x32_bf16 v[116:119], v[156:159], v[176:179], v[116:119]
	v_mfma_f32_16x16x32_bf16 v[104:107], v[148:151], v[186:189], v[104:107]
	v_mfma_f32_16x16x32_bf16 v[100:103], v[156:159], v[186:189], v[100:103]
	v_mfma_f32_16x16x32_bf16 v[88:91], v[148:151], v[194:197], v[88:91]
	v_mfma_f32_16x16x32_bf16 v[84:87], v[156:159], v[194:197], v[84:87]
	v_mfma_f32_16x16x32_bf16 v[72:75], v[148:151], v[212:215], v[72:75]
	v_mfma_f32_16x16x32_bf16 v[68:71], v[156:159], v[212:215], v[68:71]
	v_mfma_f32_16x16x32_bf16 v[120:123], v[152:155], v[180:183], v[120:123]
	v_mfma_f32_16x16x32_bf16 v[116:119], v[160:163], v[180:183], v[116:119]
	v_mfma_f32_16x16x32_bf16 v[104:107], v[152:155], v[190:193], v[104:107]
	v_mfma_f32_16x16x32_bf16 v[100:103], v[160:163], v[190:193], v[100:103]
	v_mfma_f32_16x16x32_bf16 v[88:91], v[152:155], v[208:211], v[88:91]
	v_mfma_f32_16x16x32_bf16 v[84:87], v[160:163], v[208:211], v[84:87]
	v_mfma_f32_16x16x32_bf16 v[72:75], v[152:155], v[216:219], v[72:75]
	v_mfma_f32_16x16x32_bf16 v[68:71], v[160:163], v[216:219], v[68:71]
	s_setprio 0
	s_barrier
; #define PG8_STAGE(bufoff, gbase, voff) do { _Pragma("unroll") for (int _i = 0; _i < 2; ++_i) \
;         __builtin_amdgcn_global_load_lds((const unsigned*)((const char*)(gbase) + (voff)[_i]), (LAS unsigned*)(lds + (bufoff) + ldsw + _i * 8192), 16, 0, 0); } while (0)
; #define PG8_LDA(dst, b, h) do { _Pragma("unroll") for (int m = 0; m < 4; ++m) _Pragma("unroll") for (int k = 0; k < 2; ++k) dst[m][k] = *(const LAS bf16x8*)(lds + PG8_SA(b, h) + aoff + m * 2048 + k * 1024); } while (0)
; #define PG8_MMA(ai, bj, At, Bt) do { __builtin_amdgcn_s_setprio(1); _Pragma("unroll") for (int m = 0; m < 4; ++m) _Pragma("unroll") for (int n = 0; n < 2; ++n) _Pragma("unroll") for (int k = 0; k < 2; ++k) \
;         acc[ai][bj][m][n] = __builtin_amdgcn_mfma_f32_16x16x32_bf16(Bt[n][k], At[m][k], acc[ai][bj][m][n], 0, 0, 0); __builtin_amdgcn_s_setprio(0); } while (0)
; #define PG8_WAIT_V(n) asm volatile("s_waitcnt vmcnt(" #n ")" ::: "memory")
; #define PG8_WAIT_L(n) asm volatile("s_waitcnt lgkmcnt(" #n ")" ::: "memory")
; #define PG8_BAR __builtin_amdgcn_s_barrier()
; #define PG8_SCHED __builtin_amdgcn_sched_barrier(0)
; template <class Epi, class Sched, bool HALFN = false>
; __device__ __forceinline__ void gemm_phase(LAS unsigned char* lds, const Gemm g, const Sched& S, const Epi& E, int wave_s) {
;     ...
;             PG8_LDA(At, 1, 1); PG8_STAGE(PG8_SB(1, 0), b3, voffB); PG8_STAGE(PG8_SB(1, 1), b3 + bh1, voffB); PG8_STAGE(PG8_SA(1, 0), a3, voffA);
;             PG8_WAIT_V(8); PG8_WAIT_L(0); PG8_BAR; PG8_MMA(1, 0, At, B0); if (!HALFN) PG8_MMA(1, 1, At, B1); PG8_BAR; PG8_SCHED;
;         }
	s_add_i32 s36, s53, s41
	v_lshl_add_u64 v[198:199], v[198:199], 0, s[50:51]
	s_mov_b32 m0, s36
	ds_read_b128 v[176:179], v184 offset:49152
	ds_read_b128 v[180:183], v184 offset:50176
	ds_read_b128 v[186:189], v184 offset:51200
	ds_read_b128 v[190:193], v184 offset:52224
	ds_read_b128 v[194:197], v184 offset:53248
	ds_read_b128 v[208:211], v184 offset:54272
	ds_read_b128 v[212:215], v184 offset:55296
	ds_read_b128 v[216:219], v184 offset:56320
	global_load_lds_dwordx4 v[198:199], off
	s_add_i32 m0, s36, 0x2000
	s_add_u32 s34, s34, 0x40080
	v_lshl_add_u64 v[198:199], v[202:203], 0, s[50:51]
	s_addc_u32 s35, s35, 0
	s_add_i32 s36, s66, s41
	global_load_lds_dwordx4 v[198:199], off
	v_lshl_add_u64 v[198:199], s[34:35], 0, v[166:167]
	s_mov_b32 m0, s36
	s_nop 0
	global_load_lds_dwordx4 v[198:199], off
	v_lshl_add_u64 v[198:199], s[34:35], 0, v[170:171]
	s_add_i32 m0, s36, 0x2000
	s_nop 0
	global_load_lds_dwordx4 v[198:199], off
	v_lshl_add_u64 v[198:199], v[220:221], 0, s[50:51]
	s_mov_b32 m0, s64
	s_nop 0
	global_load_lds_dwordx4 v[198:199], off
	v_lshl_add_u64 v[198:199], v[222:223], 0, s[50:51]
	s_mov_b32 m0, s65
	s_nop 0
	global_load_lds_dwordx4 v[198:199], off
	s_waitcnt vmcnt(8)
	s_waitcnt lgkmcnt(0)
	s_barrier
	s_setprio 1
	v_mfma_f32_16x16x32_bf16 v[64:67], v[132:135], v[176:179], v[64:67]
	v_mfma_f32_16x16x32_bf16 v[60:63], v[140:143], v[176:179], v[60:63]
	v_mfma_f32_16x16x32_bf16 v[48:51], v[132:135], v[186:189], v[48:51]
	v_mfma_f32_16x16x32_bf16 v[44:47], v[140:143], v[186:189], v[44:47]
	v_mfma_f32_16x16x32_bf16 v[32:35], v[132:135], v[194:197], v[32:35]
	v_mfma_f32_16x16x32_bf16 v[28:31], v[140:143], v[194:197], v[28:31]
	v_mfma_f32_16x16x32_bf16 v[14:17], v[132:135], v[212:215], v[14:17]
	v_mfma_f32_16x16x32_bf16 v[10:13], v[140:143], v[212:215], v[10:13]
	v_mfma_f32_16x16x32_bf16 v[64:67], v[136:139], v[180:183], v[64:67]
	v_mfma_f32_16x16x32_bf16 v[60:63], v[144:147], v[180:183], v[60:63]
	v_mfma_f32_16x16x32_bf16 v[48:51], v[136:139], v[190:193], v[48:51]
	v_mfma_f32_16x16x32_bf16 v[44:47], v[144:147], v[190:193], v[44:47]
	v_mfma_f32_16x16x32_bf16 v[32:35], v[136:139], v[208:211], v[32:35]
	v_mfma_f32_16x16x32_bf16 v[28:31], v[144:147], v[208:211], v[28:31]
	v_mfma_f32_16x16x32_bf16 v[14:17], v[136:139], v[216:219], v[14:17]
	v_mfma_f32_16x16x32_bf16 v[10:13], v[144:147], v[216:219], v[10:13]
	s_setprio 0
	s_setprio 1
	v_mfma_f32_16x16x32_bf16 v[56:59], v[148:151], v[176:179], v[56:59]
	v_mfma_f32_16x16x32_bf16 v[52:55], v[156:159], v[176:179], v[52:55]
	v_mfma_f32_16x16x32_bf16 v[40:43], v[148:151], v[186:189], v[40:43]
	v_mfma_f32_16x16x32_bf16 v[36:39], v[156:159], v[186:189], v[36:39]
	v_mfma_f32_16x16x32_bf16 v[24:27], v[148:151], v[194:197], v[24:27]
	v_mfma_f32_16x16x32_bf16 v[20:23], v[156:159], v[194:197], v[20:23]
	v_mfma_f32_16x16x32_bf16 v[6:9], v[148:151], v[212:215], v[6:9]
	v_mfma_f32_16x16x32_bf16 v[2:5], v[156:159], v[212:215], v[2:5]
	v_mfma_f32_16x16x32_bf16 v[56:59], v[152:155], v[180:183], v[56:59]
	v_mfma_f32_16x16x32_bf16 v[52:55], v[160:163], v[180:183], v[52:55]
	v_mfma_f32_16x16x32_bf16 v[40:43], v[152:155], v[190:193], v[40:43]
	v_mfma_f32_16x16x32_bf16 v[36:39], v[160:163], v[190:193], v[36:39]
	v_mfma_f32_16x16x32_bf16 v[24:27], v[152:155], v[208:211], v[24:27]
	v_mfma_f32_16x16x32_bf16 v[20:23], v[160:163], v[208:211], v[20:23]
	v_mfma_f32_16x16x32_bf16 v[6:9], v[152:155], v[216:219], v[6:9]
	v_mfma_f32_16x16x32_bf16 v[2:5], v[160:163], v[216:219], v[2:5]
	s_setprio 0
	s_add_i32 s52, s52, 2
	s_add_u32 s6, s6, 0x100
	s_addc_u32 s7, s7, 0
	s_add_u32 s42, s42, 0x100
	s_addc_u32 s48, s48, 0
	s_cmp_gt_u32 s52, 13
	s_barrier
	s_cbranch_scc0 .LBB0_985
	s_and_b64 vcc, exec, s[20:21]
	s_cbranch_vccz .LBB0_988
	s_barrier
